# baseline (speedup 1.0000x reference)
; template <int PASS> __device__ void phase_lru(const Params& P, unsigned char* smem) {
;     ...
;         bf16x8 bA[4][2], bX[4][2];
; #pragma unroll
;         for (int ks = 0; ks < 4; ++ks)
; #pragma unroll
;             for (int tn = 0; tn < 2; ++tn) { bA[ks][tn] = *(const bf16x8*)(wA + tn * 16 * 128 + ks * 32); bX[ks][tn] = *(const bf16x8*)(wX + tn * 16 * 128 + ks * 32); }
;         asm volatile("" ::: "memory");
;         const bool has_next = (g + 1) < nloc * 4;
;         LruUnit UN = U;
;         if (has_next) {
;             if (step == 3) { UN = lru_decode((int)blockIdx.x + ((g + 1) >> 2) * (int)gridDim.x); LRU_LOADW(UN); }
.LBB0_352:
	v_lshl_add_u32 v224, s2, 3, v146
	v_lshlrev_b32_e32 v224, 14, v224
	v_and_b32_e32 v232, 63, v144
	v_lshl_add_u32 v224, v232, 4, v224
	v_mov_b32_e32 v225, 0
	v_lshl_add_u64 v[224:225], s[90:91], 0, v[224:225]
	v_mov_b32_e32 v232, 0x23000000
	v_mov_b32_e32 v233, 0
	v_lshl_add_u64 v[224:225], v[224:225], 0, v[232:233]
	v_mov_b32_e32 v232, 0x1000
	v_lshl_add_u64 v[226:227], v[224:225], 0, v[232:233]
	v_lshl_add_u64 v[228:229], v[226:227], 0, v[232:233]
	v_lshl_add_u64 v[230:231], v[228:229], 0, v[232:233]
	s_cmp_lg_u32 s51, 0
	s_cbranch_scc1 .Llru1_wready
	v_add_co_u32_e32 v56, vcc, 0x1000, v162
	s_nop 0
	v_addc_co_u32_e32 v57, vcc, 0, v163, vcc
	v_add_co_u32_e32 v60, vcc, 0x1000, v164
	s_nop 0
	v_addc_co_u32_e32 v61, vcc, 0, v165, vcc
	global_load_dwordx4 v[116:119], v[162:163], off
	global_load_dwordx4 v[104:107], v[162:163], off offset:64
	global_load_dwordx4 v[120:123], v[164:165], off
	global_load_dwordx4 v[100:103], v[164:165], off offset:64
	global_load_dwordx4 v[112:115], v[56:57], off
	global_load_dwordx4 v[96:99], v[56:57], off offset:64
	global_load_dwordx4 v[108:111], v[60:61], off
	global_load_dwordx4 v[92:95], v[60:61], off offset:64
	global_load_dwordx4 v[88:91], v[162:163], off offset:128
	global_load_dwordx4 v[80:83], v[162:163], off offset:192
	global_load_dwordx4 v[84:87], v[164:165], off offset:128
	global_load_dwordx4 v[76:79], v[164:165], off offset:192
	global_load_dwordx4 v[72:75], v[56:57], off offset:128
	global_load_dwordx4 v[64:67], v[56:57], off offset:192
	global_load_dwordx4 v[68:71], v[60:61], off offset:128
	s_nop 0
	global_load_dwordx4 v[60:63], v[60:61], off offset:192
	s_waitcnt vmcnt(0)
	global_store_dwordx4 v[224:225], v[116:119], off
	global_store_dwordx4 v[224:225], v[104:107], off offset:1024
	global_store_dwordx4 v[224:225], v[120:123], off offset:2048
	global_store_dwordx4 v[224:225], v[100:103], off offset:3072
	global_store_dwordx4 v[226:227], v[112:115], off
	global_store_dwordx4 v[226:227], v[96:99], off offset:1024
	global_store_dwordx4 v[226:227], v[108:111], off offset:2048
	global_store_dwordx4 v[226:227], v[92:95], off offset:3072
	global_store_dwordx4 v[228:229], v[88:91], off
	global_store_dwordx4 v[228:229], v[80:83], off offset:1024
	global_store_dwordx4 v[228:229], v[84:87], off offset:2048
	global_store_dwordx4 v[228:229], v[76:79], off offset:3072
	global_store_dwordx4 v[230:231], v[72:75], off
	global_store_dwordx4 v[230:231], v[64:67], off offset:1024
	global_store_dwordx4 v[230:231], v[68:71], off offset:2048
	global_store_dwordx4 v[230:231], v[60:63], off offset:3072
	s_waitcnt vmcnt(0)
.Llru1_wready:
	s_add_i32 s50, s51, 1
	s_cmp_lt_i32 s50, s13
	global_load_dwordx4 v[116:119], v[224:225], off
	global_load_dwordx4 v[104:107], v[224:225], off offset:1024
	global_load_dwordx4 v[120:123], v[224:225], off offset:2048
	global_load_dwordx4 v[100:103], v[224:225], off offset:3072
	global_load_dwordx4 v[112:115], v[226:227], off
	global_load_dwordx4 v[96:99], v[226:227], off offset:1024
	global_load_dwordx4 v[108:111], v[226:227], off offset:2048
	global_load_dwordx4 v[92:95], v[226:227], off offset:3072
	global_load_dwordx4 v[88:91], v[228:229], off
	global_load_dwordx4 v[80:83], v[228:229], off offset:1024
	global_load_dwordx4 v[84:87], v[228:229], off offset:2048
	global_load_dwordx4 v[76:79], v[228:229], off offset:3072
	global_load_dwordx4 v[72:75], v[230:231], off
	global_load_dwordx4 v[64:67], v[230:231], off offset:1024
	global_load_dwordx4 v[68:71], v[230:231], off offset:2048
	global_load_dwordx4 v[60:63], v[230:231], off offset:3072
	s_cselect_b64 s[44:45], -1, 0
	s_cmp_ge_i32 s50, s13
	s_cbranch_scc1 .LBB0_366
	s_cmp_eq_u32 s9, 3
	s_mov_b64 s[0:1], -1
	s_cbranch_scc1 .LBB0_355
	s_lshl_b32 s10, s3, 7
	s_mov_b64 s[0:1], 0

; template <int PASS> __device__ void phase_lru(const Params& P, unsigned char* smem) {
;     ...
;         bf16x8 bA[4][2], bX[4][2];
; #pragma unroll
;         for (int ks = 0; ks < 4; ++ks)
; #pragma unroll
;             for (int tn = 0; tn < 2; ++tn) { bA[ks][tn] = *(const bf16x8*)(wA + tn * 16 * 128 + ks * 32); bX[ks][tn] = *(const bf16x8*)(wX + tn * 16 * 128 + ks * 32); }
;         asm volatile("" ::: "memory");
;         const bool has_next = (g + 1) < nloc * 4;
;         LruUnit UN = U;
;         if (has_next) {
;             if (step == 3) { UN = lru_decode((int)blockIdx.x + ((g + 1) >> 2) * (int)gridDim.x); LRU_LOADW(UN); }
.LBB0_473:
	v_lshl_add_u32 v238, s2, 3, v146
	v_lshlrev_b32_e32 v238, 14, v238
	v_and_b32_e32 v246, 63, v144
	v_lshl_add_u32 v238, v246, 4, v238
	v_mov_b32_e32 v239, 0
	v_lshl_add_u64 v[238:239], s[90:91], 0, v[238:239]
	v_mov_b32_e32 v246, 0x23000000
	v_mov_b32_e32 v247, 0
	v_lshl_add_u64 v[238:239], v[238:239], 0, v[246:247]
	v_mov_b32_e32 v246, 0x1000
	v_lshl_add_u64 v[240:241], v[238:239], 0, v[246:247]
	v_lshl_add_u64 v[242:243], v[240:241], 0, v[246:247]
	v_lshl_add_u64 v[244:245], v[242:243], 0, v[246:247]
	s_add_i32 s83, s83, 1
	s_cmp_lt_i32 s83, s47
	global_load_dwordx4 v[128:131], v[238:239], off
	global_load_dwordx4 v[112:115], v[238:239], off offset:1024
	global_load_dwordx4 v[132:135], v[238:239], off offset:2048
	global_load_dwordx4 v[116:119], v[238:239], off offset:3072
	global_load_dwordx4 v[136:139], v[240:241], off
	global_load_dwordx4 v[120:123], v[240:241], off offset:1024
	global_load_dwordx4 v[140:143], v[240:241], off offset:2048
	global_load_dwordx4 v[124:127], v[240:241], off offset:3072
	global_load_dwordx4 v[88:91], v[242:243], off
	global_load_dwordx4 v[80:83], v[242:243], off offset:1024
	global_load_dwordx4 v[92:95], v[242:243], off offset:2048
	global_load_dwordx4 v[84:87], v[242:243], off offset:3072
	global_load_dwordx4 v[104:107], v[244:245], off
	global_load_dwordx4 v[96:99], v[244:245], off offset:1024
	global_load_dwordx4 v[108:111], v[244:245], off offset:2048
	global_load_dwordx4 v[100:103], v[244:245], off offset:3072
	s_cselect_b64 s[8:9], -1, 0
	s_cmp_ge_i32 s83, s47
	s_cbranch_scc1 .LBB0_495
	s_cmp_eq_u32 s84, 3
	s_mov_b64 s[0:1], -1
	s_cbranch_scc1 .LBB0_476
	s_lshl_b32 s42, s45, 7
	s_mov_b64 s[0:1], 0
